# diff-attn loop: QK segments regenerated with 8-deep K-fragment read pipeline, exps up front under LDS latency
# speedup vs baseline: 1.0173x; 1.0061x over previous
; __device__ __forceinline__ void finishSM(f32x16& p0, f32x16& p1, float alpha, float& l_reg, bf16x8& pa0, bf16x8& pa1, bf16x8& pa2, bf16x8& pa3) {
;     for (int r = 0; r < 16; ++r) p1[r] = __builtin_amdgcn_exp2f(p1[r]);
;     float ps = 0; for (int r = 0; r < 16; ++r) ps += p0[r]; for (int r = 0; r < 16; ++r) ps += p1[r];
;     { auto rr = __builtin_amdgcn_permlane32_swap(__float_as_uint(ps), __float_as_uint(ps), false, false);
;       ps = __uint_as_float(rr[0]) + __uint_as_float(rr[1]); }
;     l_reg = l_reg * alpha + ps;
;     ...
;     PK4(p0, 0, pa0); PK4(p0, 8, pa1); PK4(p1, 0, pa2); PK4(p1, 8, pa3);
;     ...
; }
; template <int KB, bool SK>
; __device__ __forceinline__ void qkt(f32x16& p0, f32x16& p1, const char* K_lds, int r32, int hi, const bf16x8* qr, bool act) {
;     if (SK && !act) { const float NEG = -__builtin_inff();
; #pragma unroll
;         for (int r = 0; r < 16; ++r) { p0[r] = NEG; p1[r] = NEG; } return; }
;     p0 = f32x16{}; p1 = f32x16{};
;     const char* kb[4];
; #pragma unroll
;     for (int dd = 0; dd < 4; ++dd) kb[dd] = K_lds + KB * SHM_K + KSWZ(r32, (dd * 16 + hi * 8) * 2);
; #pragma unroll
;     for (int d0 = 0; d0 < 8; ++d0) { const char* a = kb[d0 & 3] + (d0 >> 2) * 128;
;         bf16x8 b0 = *reinterpret_cast<const bf16x8*>(a);
;         bf16x8 b1 = *reinterpret_cast<const bf16x8*>(a + 32 * 256);
;         const bf16x8 qf = qr[d0];
;         p0 = __builtin_amdgcn_mfma_f32_32x32x16_bf16(b0, qf, p0, 0, 0, 0);
;         p1 = __builtin_amdgcn_mfma_f32_32x32x16_bf16(b1, qf, p1, 0, 0, 0); }
; }
.LBB0_1129:
	ds_read_b128 v[180:183], v211 offset:49152
	ds_read_b128 v[184:187], v211 offset:57344
	ds_read_b128 v[188:191], v212 offset:49152
	ds_read_b128 v[228:231], v212 offset:57344
	ds_read_b128 v[232:235], v213 offset:49152
	ds_read_b128 v[236:239], v213 offset:57344
	ds_read_b128 v[240:243], v214 offset:49152
	ds_read_b128 v[244:247], v214 offset:57344
	v_exp_f32_e32 v126, v126
	v_exp_f32_e32 v127, v127
	v_exp_f32_e32 v124, v124
	v_exp_f32_e32 v125, v125
	v_exp_f32_e32 v120, v120
	v_exp_f32_e32 v121, v121
	v_exp_f32_e32 v116, v116
	v_exp_f32_e32 v117, v117
	v_exp_f32_e32 v114, v114
	v_exp_f32_e32 v115, v115
	v_exp_f32_e32 v128, v128
	v_exp_f32_e32 v129, v129
	v_exp_f32_e32 v122, v122
	v_exp_f32_e32 v123, v123
	v_exp_f32_e32 v118, v118
	v_exp_f32_e32 v119, v119
	s_add_i32 s4, s26, 0xffffff81
	s_sub_i32 s5, s26, 64
	s_waitcnt lgkmcnt(7)
	v_mfma_f32_32x32x16_bf16 v[86:101], v[180:183], v[158:161], 0
	ds_read_b128 v[180:183], v211 offset:49280
	v_add_f32_e32 v179, 0, v170
	v_add_f32_e32 v179, v171, v179
	v_add_f32_e32 v179, v172, v179
	v_add_f32_e32 v179, v173, v179
	s_waitcnt lgkmcnt(7)
	v_mfma_f32_32x32x16_bf16 v[70:85], v[184:187], v[158:161], 0
	ds_read_b128 v[184:187], v211 offset:57472
	v_add_f32_e32 v179, v174, v179
	v_add_f32_e32 v179, v176, v179
	v_add_f32_e32 v179, v175, v179
	v_add_f32_e32 v179, v177, v179
	s_waitcnt lgkmcnt(7)
	v_mfma_f32_32x32x16_bf16 v[86:101], v[188:191], v[154:157], v[86:101]
	ds_read_b128 v[188:191], v212 offset:49280
	v_add_f32_e32 v179, v162, v179
	v_add_f32_e32 v179, v163, v179
	v_add_f32_e32 v110, v164, v179
	v_add_f32_e32 v110, v166, v110
	s_waitcnt lgkmcnt(7)
	v_mfma_f32_32x32x16_bf16 v[70:85], v[228:231], v[154:157], v[70:85]
	ds_read_b128 v[228:231], v212 offset:57472
	v_add_f32_e32 v110, v165, v110
	v_add_f32_e32 v110, v167, v110
	v_add_f32_e32 v110, v168, v110
	v_add_f32_e32 v110, v169, v110
	s_waitcnt lgkmcnt(7)
	v_mfma_f32_32x32x16_bf16 v[86:101], v[232:235], v[150:153], v[86:101]
	ds_read_b128 v[232:235], v213 offset:49280
	v_add_f32_e32 v110, v126, v110
	v_add_f32_e32 v102, v127, v110
	v_add_f32_e32 v102, v124, v102
	v_add_f32_e32 v102, v125, v102
	s_waitcnt lgkmcnt(7)
	v_mfma_f32_32x32x16_bf16 v[70:85], v[236:239], v[150:153], v[70:85]
	ds_read_b128 v[236:239], v213 offset:57472
	v_add_f32_e32 v102, v120, v102
	v_add_f32_e32 v102, v121, v102
	v_add_f32_e32 v102, v116, v102
	v_add_f32_e32 v102, v117, v102
	s_waitcnt lgkmcnt(7)
	v_mfma_f32_32x32x16_bf16 v[86:101], v[240:243], v[134:137], v[86:101]
	ds_read_b128 v[240:243], v214 offset:49280
	v_add_f32_e32 v102, v114, v102
	v_add_f32_e32 v102, v115, v102
	v_add_f32_e32 v102, v128, v102
	v_add_f32_e32 v102, v129, v102
	s_waitcnt lgkmcnt(7)
	v_mfma_f32_32x32x16_bf16 v[70:85], v[244:247], v[134:137], v[70:85]
	ds_read_b128 v[244:247], v214 offset:57472
	v_add_f32_e32 v102, v122, v102
	v_add_f32_e32 v102, v123, v102
	v_add_f32_e32 v102, v118, v102
	v_add_f32_e32 v223, v119, v102
	s_waitcnt lgkmcnt(7)
	v_mfma_f32_32x32x16_bf16 v[86:101], v[180:183], v[138:141], v[86:101]
	v_mov_b32_e32 v224, v223
	s_nop 1
	v_permlane32_swap_b32_e32 v223, v224
	v_cvt_pk_bf16_f32 v102, v170, v171
	v_cvt_pk_bf16_f32 v103, v172, v173
	s_waitcnt lgkmcnt(6)
	v_mfma_f32_32x32x16_bf16 v[70:85], v[184:187], v[138:141], v[70:85]
	v_cvt_pk_bf16_f32 v104, v174, v176
	v_cvt_pk_bf16_f32 v105, v175, v177
	v_cvt_pk_bf16_f32 v66, v162, v163
	v_cvt_pk_bf16_f32 v67, v164, v166
	s_waitcnt lgkmcnt(5)
	v_mfma_f32_32x32x16_bf16 v[86:101], v[188:191], v[142:145], v[86:101]
	v_cvt_pk_bf16_f32 v68, v165, v167
	v_cvt_pk_bf16_f32 v69, v168, v169
	v_cvt_pk_bf16_f32 v106, v126, v127
	s_waitcnt lgkmcnt(4)
	v_mfma_f32_32x32x16_bf16 v[70:85], v[228:231], v[142:145], v[70:85]
	v_cvt_pk_bf16_f32 v107, v124, v125
	v_cvt_pk_bf16_f32 v108, v120, v121
	v_cvt_pk_bf16_f32 v109, v116, v117
	s_waitcnt lgkmcnt(3)
	v_mfma_f32_32x32x16_bf16 v[86:101], v[232:235], v[146:149], v[86:101]
	v_cvt_pk_bf16_f32 v110, v114, v115
	v_cvt_pk_bf16_f32 v111, v128, v129
	v_cvt_pk_bf16_f32 v112, v122, v123
	s_waitcnt lgkmcnt(2)
	v_mfma_f32_32x32x16_bf16 v[70:85], v[236:239], v[146:149], v[70:85]
	v_cvt_pk_bf16_f32 v113, v118, v119
	s_nop 1
	v_permlane32_swap_b32_e32 v102, v104
	v_permlane32_swap_b32_e32 v103, v105
	s_waitcnt lgkmcnt(1)
	v_mfma_f32_32x32x16_bf16 v[86:101], v[240:243], v[130:133], v[86:101]
	v_permlane32_swap_b32_e32 v66, v68
	v_permlane32_swap_b32_e32 v67, v69
	v_permlane32_swap_b32_e32 v106, v108
	s_waitcnt lgkmcnt(0)
	v_mfma_f32_32x32x16_bf16 v[70:85], v[244:247], v[130:133], v[70:85]
	v_permlane32_swap_b32_e32 v107, v109
	v_permlane32_swap_b32_e32 v110, v112
	v_permlane32_swap_b32_e32 v111, v113
	v_lshlrev_b64 v[114:115], 1, v[194:195]
	v_add_u32_e32 v118, 0x1000, v194
	v_mov_b32_e32 v119, v195
	v_lshl_add_u64 v[116:117], s[42:43], 0, v[114:115]
	v_lshlrev_b64 v[118:119], 1, v[118:119]
	v_lshl_add_u64 v[114:115], s[22:23], 0, v[114:115]
	v_lshl_add_u64 v[120:121], s[42:43], 0, v[118:119]
	global_load_dwordx4 v[162:165], v[116:117], off
	global_load_dwordx4 v[166:169], v[120:121], off
	v_lshl_add_u64 v[116:117], s[22:23], 0, v[118:119]
	global_load_dwordx4 v[170:173], v[114:115], off
	global_load_dwordx4 v[174:177], v[116:117], off
	s_cmp_le_i32 s5, s13
	s_cselect_b64 s[52:53], -1, 0
	s_cmp_gt_i32 s4, s15
	s_cselect_b64 s[4:5], -1, 0
	s_and_b64 s[4:5], s[52:53], s[4:5]
	s_and_b64 vcc, exec, s[4:5]
	v_add_u32_e32 v226, s80, v222
	ds_read_b64_tr_b16 v[114:115], v202 offset:0x0
	ds_read_b64_tr_b16 v[116:117], v202 offset:0x800
	ds_read_b64_tr_b16 v[118:119], v202 offset:0x1000
	ds_read_b64_tr_b16 v[120:121], v202 offset:0x1800
	ds_read_b64_tr_b16 v[122:123], v202 offset:0x2000
	ds_read_b64_tr_b16 v[124:125], v202 offset:0x2800
	ds_read_b64_tr_b16 v[126:127], v202 offset:0x3000
	ds_read_b64_tr_b16 v[128:129], v202 offset:0x3800
	s_cbranch_vccnz .Lh1_nomask
; __device__ __forceinline__ void mask_tile(f32x16& p0, f32x16& p1, int dq, unsigned W) {
;     const float NEG = -__builtin_inff();
; #pragma unroll
;     for (int r = 0; r < 16; ++r) {
;         const int c = (r & 3) + 8 * (r >> 2);
;         if ((unsigned)(dq - c) >= W) p0[r] = NEG;
;         if ((unsigned)(dq - c - 32) >= W) p1[r] = NEG;
;     }
; }
	v_subrev_u32_e32 v240, 64, v226
	v_cmp_gt_u32_e32 vcc, s85, v240
	v_add_u32_e32 v240, 0xffffffa0, v226
	s_nop 0
	v_cndmask_b32_e32 v86, v215, v86, vcc
	v_cmp_gt_u32_e32 vcc, s85, v240
	v_add_u32_e32 v240, 0xffffffbf, v226
	s_nop 0
	v_cndmask_b32_e32 v70, v215, v70, vcc
	v_cmp_gt_u32_e32 vcc, s85, v240
	v_add_u32_e32 v240, 0xffffff9f, v226
	s_nop 0
	v_cndmask_b32_e32 v87, v215, v87, vcc
	v_cmp_gt_u32_e32 vcc, s85, v240
	v_add_u32_e32 v240, 0xffffffbe, v226
	s_nop 0
	v_cndmask_b32_e32 v71, v215, v71, vcc
	v_cmp_gt_u32_e32 vcc, s85, v240
	v_add_u32_e32 v240, 0xffffff9e, v226
	s_nop 0
	v_cndmask_b32_e32 v88, v215, v88, vcc
	v_cmp_gt_u32_e32 vcc, s85, v240
	v_add_u32_e32 v240, 0xffffffbd, v226
	s_nop 0
	v_cndmask_b32_e32 v72, v215, v72, vcc
	v_cmp_gt_u32_e32 vcc, s85, v240
	v_add_u32_e32 v240, 0xffffff9d, v226
	s_nop 0
	v_cndmask_b32_e32 v89, v215, v89, vcc
	v_cmp_gt_u32_e32 vcc, s85, v240
	v_add_u32_e32 v240, 0xffffffb8, v226
	s_nop 0
	v_cndmask_b32_e32 v73, v215, v73, vcc
	v_cmp_gt_u32_e32 vcc, s85, v240
	v_add_u32_e32 v240, 0xffffff98, v226
	s_nop 0
	v_cndmask_b32_e32 v90, v215, v90, vcc
	v_cmp_gt_u32_e32 vcc, s85, v240
	v_add_u32_e32 v240, 0xffffffb7, v226
	s_nop 0
	v_cndmask_b32_e32 v74, v215, v74, vcc
	v_cmp_gt_u32_e32 vcc, s85, v240
	v_add_u32_e32 v240, 0xffffff97, v226
	s_nop 0
	v_cndmask_b32_e32 v91, v215, v91, vcc
	v_cmp_gt_u32_e32 vcc, s85, v240
	v_add_u32_e32 v240, 0xffffffb6, v226
	s_nop 0
	v_cndmask_b32_e32 v75, v215, v75, vcc
	v_cmp_gt_u32_e32 vcc, s85, v240
	v_add_u32_e32 v240, 0xffffff96, v226
	s_nop 0
	v_cndmask_b32_e32 v92, v215, v92, vcc
	v_cmp_gt_u32_e32 vcc, s85, v240
	v_add_u32_e32 v240, 0xffffffb5, v226
	s_nop 0
	v_cndmask_b32_e32 v76, v215, v76, vcc
	v_cmp_gt_u32_e32 vcc, s85, v240
	v_add_u32_e32 v240, 0xffffff95, v226
	s_nop 0
	v_cndmask_b32_e32 v93, v215, v93, vcc
	v_cmp_gt_u32_e32 vcc, s85, v240
	v_add_u32_e32 v240, 0xffffffb0, v226
	s_nop 0
	v_cndmask_b32_e32 v77, v215, v77, vcc
	v_cmp_gt_u32_e32 vcc, s85, v240
	v_add_u32_e32 v240, 0xffffff90, v226
	s_nop 0
	v_cndmask_b32_e32 v94, v215, v94, vcc
	v_cmp_gt_u32_e32 vcc, s85, v240
	v_add_u32_e32 v240, 0xffffffaf, v226
	s_nop 0
	v_cndmask_b32_e32 v78, v215, v78, vcc
	v_cmp_gt_u32_e32 vcc, s85, v240
	v_add_u32_e32 v240, 0xffffff8f, v226
	s_nop 0
	v_cndmask_b32_e32 v95, v215, v95, vcc
	v_cmp_gt_u32_e32 vcc, s85, v240
	v_add_u32_e32 v240, 0xffffffae, v226
	s_nop 0
	v_cndmask_b32_e32 v79, v215, v79, vcc
	v_cmp_gt_u32_e32 vcc, s85, v240
	v_add_u32_e32 v240, 0xffffff8e, v226
	s_nop 0
	v_cndmask_b32_e32 v96, v215, v96, vcc
	v_cmp_gt_u32_e32 vcc, s85, v240
	v_add_u32_e32 v240, 0xffffffad, v226
	s_nop 0
	v_cndmask_b32_e32 v80, v215, v80, vcc
	v_cmp_gt_u32_e32 vcc, s85, v240
	v_add_u32_e32 v240, 0xffffff8d, v226
	s_nop 0
	v_cndmask_b32_e32 v97, v215, v97, vcc
	v_cmp_gt_u32_e32 vcc, s85, v240
	v_add_u32_e32 v240, 0xffffffa8, v226
	s_nop 0
	v_cndmask_b32_e32 v81, v215, v81, vcc
	v_cmp_gt_u32_e32 vcc, s85, v240
	v_add_u32_e32 v240, 0xffffff88, v226
	s_nop 0
	v_cndmask_b32_e32 v98, v215, v98, vcc
	v_cmp_gt_u32_e32 vcc, s85, v240
	v_add_u32_e32 v240, 0xffffffa7, v226
	s_nop 0
	v_cndmask_b32_e32 v82, v215, v82, vcc
	v_cmp_gt_u32_e32 vcc, s85, v240
	v_add_u32_e32 v240, 0xffffff87, v226
	s_nop 0
	v_cndmask_b32_e32 v99, v215, v99, vcc
	v_cmp_gt_u32_e32 vcc, s85, v240
	v_add_u32_e32 v240, 0xffffffa6, v226
	s_nop 0
	v_cndmask_b32_e32 v83, v215, v83, vcc
	v_cmp_gt_u32_e32 vcc, s85, v240
	v_add_u32_e32 v240, 0xffffff86, v226
	s_nop 0
	v_cndmask_b32_e32 v100, v215, v100, vcc
	v_cmp_gt_u32_e32 vcc, s85, v240
	v_add_u32_e32 v240, 0xffffffa5, v226
	s_nop 0
	v_cndmask_b32_e32 v84, v215, v84, vcc
	v_cmp_gt_u32_e32 vcc, s85, v240
	v_add_u32_e32 v240, 0xffffff85, v226
	s_nop 0
	v_cndmask_b32_e32 v101, v215, v101, vcc
	v_cmp_gt_u32_e32 vcc, s85, v240
	s_nop 1
	v_cndmask_b32_e32 v85, v215, v85, vcc

; __device__ __forceinline__ void partialSM(f32x16& p0, f32x16& p1, float& m_reg, float& mn, float& alpha) {
;     ...
;     for (int r = 0; r < 16; ++r) p0[r] = __builtin_amdgcn_exp2f(p0[r]);
; }
; __device__ __forceinline__ void finishSM(f32x16& p0, f32x16& p1, float alpha, float& l_reg, bf16x8& pa0, bf16x8& pa1, bf16x8& pa2, bf16x8& pa3) {
;     for (int r = 0; r < 16; ++r) p1[r] = __builtin_amdgcn_exp2f(p1[r]);
;     float ps = 0; for (int r = 0; r < 16; ++r) ps += p0[r]; for (int r = 0; r < 16; ++r) ps += p1[r];
;     { auto rr = __builtin_amdgcn_permlane32_swap(__float_as_uint(ps), __float_as_uint(ps), false, false);
;       ps = __uint_as_float(rr[0]) + __uint_as_float(rr[1]); }
;     l_reg = l_reg * alpha + ps;
;     ...
;     PK4(p0, 0, pa0); PK4(p0, 8, pa1); PK4(p1, 0, pa2); PK4(p1, 8, pa3);
;     ...
; }
; template <int KB, bool SK>
; __device__ __forceinline__ void qkt(f32x16& p0, f32x16& p1, const char* K_lds, int r32, int hi, const bf16x8* qr, bool act) {
;     if (SK && !act) { const float NEG = -__builtin_inff();
; #pragma unroll
;         for (int r = 0; r < 16; ++r) { p0[r] = NEG; p1[r] = NEG; } return; }
;     p0 = f32x16{}; p1 = f32x16{};
;     const char* kb[4];
; #pragma unroll
;     for (int dd = 0; dd < 4; ++dd) kb[dd] = K_lds + KB * SHM_K + KSWZ(r32, (dd * 16 + hi * 8) * 2);
; #pragma unroll
;     for (int d0 = 0; d0 < 8; ++d0) { const char* a = kb[d0 & 3] + (d0 >> 2) * 128;
;         bf16x8 b0 = *reinterpret_cast<const bf16x8*>(a);
;         bf16x8 b1 = *reinterpret_cast<const bf16x8*>(a + 32 * 256);
;         const bf16x8 qf = qr[d0];
;         p0 = __builtin_amdgcn_mfma_f32_32x32x16_bf16(b0, qf, p0, 0, 0, 0);
;         p1 = __builtin_amdgcn_mfma_f32_32x32x16_bf16(b1, qf, p1, 0, 0, 0); }
; }
.Lh1_noresc:
	v_exp_f32_e32 v66, v228
	v_exp_f32_e32 v67, v229
	v_exp_f32_e32 v68, v230
	v_exp_f32_e32 v69, v231
	v_exp_f32_e32 v70, v232
	v_exp_f32_e32 v71, v233
	v_exp_f32_e32 v72, v234
	v_exp_f32_e32 v73, v235
	v_exp_f32_e32 v74, v236
	v_exp_f32_e32 v75, v237
	v_exp_f32_e32 v76, v238
	v_exp_f32_e32 v77, v239
	v_exp_f32_e32 v78, v98
	v_exp_f32_e32 v79, v99
	v_exp_f32_e32 v80, v100
	v_exp_f32_e32 v81, v101
	s_waitcnt lgkmcnt(0)
	s_barrier
	ds_read_b128 v[162:165], v211 offset:32768
	ds_read_b128 v[166:169], v211 offset:40960
	ds_read_b128 v[170:173], v212 offset:32768
	ds_read_b128 v[174:177], v212 offset:40960
	ds_read_b128 v[230:233], v213 offset:32768
	ds_read_b128 v[234:237], v213 offset:40960
	ds_read_b128 v[238:241], v214 offset:32768
	ds_read_b128 v[242:245], v214 offset:40960
	v_exp_f32_e32 v82, v86
	v_exp_f32_e32 v83, v95
	v_exp_f32_e32 v84, v96
	v_exp_f32_e32 v85, v97
	v_exp_f32_e32 v86, v179
	v_exp_f32_e32 v87, v87
	v_exp_f32_e32 v88, v88
	v_exp_f32_e32 v89, v89
	v_exp_f32_e32 v90, v90
	v_exp_f32_e32 v91, v91
	v_exp_f32_e32 v92, v92
	v_exp_f32_e32 v93, v93
	v_exp_f32_e32 v94, v94
	v_exp_f32_e32 v95, v180
	v_exp_f32_e32 v96, v181
	v_exp_f32_e32 v97, v178
	s_waitcnt lgkmcnt(7)
	v_mfma_f32_32x32x16_bf16 v[114:129], v[162:165], v[158:161], 0
	ds_read_b128 v[162:165], v211 offset:32896
	v_add_f32_e32 v178, 0, v66
	v_add_f32_e32 v178, v67, v178
	v_add_f32_e32 v178, v68, v178
	v_add_f32_e32 v178, v69, v178
	s_waitcnt lgkmcnt(7)
	v_mfma_f32_32x32x16_bf16 v[98:113], v[166:169], v[158:161], 0
	ds_read_b128 v[166:169], v211 offset:41088
	v_add_f32_e32 v178, v70, v178
	v_add_f32_e32 v178, v71, v178
	v_add_f32_e32 v178, v72, v178
	v_add_f32_e32 v178, v73, v178
	s_waitcnt lgkmcnt(7)
	v_mfma_f32_32x32x16_bf16 v[114:129], v[170:173], v[154:157], v[114:129]
	ds_read_b128 v[170:173], v212 offset:32896
	v_add_f32_e32 v178, v74, v178
	v_add_f32_e32 v178, v75, v178
	v_add_f32_e32 v178, v76, v178
	v_add_f32_e32 v178, v77, v178
	s_waitcnt lgkmcnt(7)
	v_mfma_f32_32x32x16_bf16 v[98:113], v[174:177], v[154:157], v[98:113]
	ds_read_b128 v[174:177], v212 offset:41088
	v_add_f32_e32 v178, v78, v178
	v_add_f32_e32 v178, v79, v178
	v_add_f32_e32 v178, v80, v178
	v_add_f32_e32 v178, v81, v178
	s_waitcnt lgkmcnt(7)
	v_mfma_f32_32x32x16_bf16 v[114:129], v[230:233], v[150:153], v[114:129]
	ds_read_b128 v[230:233], v213 offset:32896
	v_add_f32_e32 v178, v82, v178
	v_add_f32_e32 v178, v83, v178
	v_add_f32_e32 v178, v84, v178
	v_add_f32_e32 v178, v85, v178
	s_waitcnt lgkmcnt(7)
	v_mfma_f32_32x32x16_bf16 v[98:113], v[234:237], v[150:153], v[98:113]
	ds_read_b128 v[234:237], v213 offset:41088
	v_add_f32_e32 v178, v86, v178
	v_add_f32_e32 v178, v87, v178
	v_add_f32_e32 v178, v88, v178
	v_add_f32_e32 v178, v89, v178
	s_waitcnt lgkmcnt(7)
	v_mfma_f32_32x32x16_bf16 v[114:129], v[238:241], v[134:137], v[114:129]
	ds_read_b128 v[238:241], v214 offset:32896
	v_add_f32_e32 v178, v90, v178
	v_add_f32_e32 v178, v91, v178
	v_add_f32_e32 v178, v92, v178
	v_add_f32_e32 v178, v93, v178
	s_waitcnt lgkmcnt(7)
	v_mfma_f32_32x32x16_bf16 v[98:113], v[242:245], v[134:137], v[98:113]
	ds_read_b128 v[242:245], v214 offset:41088
	v_add_f32_e32 v178, v94, v178
	v_add_f32_e32 v178, v95, v178
	v_add_f32_e32 v178, v96, v178
	v_add_f32_e32 v228, v97, v178
	s_waitcnt lgkmcnt(7)
	v_mfma_f32_32x32x16_bf16 v[114:129], v[162:165], v[138:141], v[114:129]
	v_mov_b32_e32 v229, v228
	s_nop 1
	v_permlane32_swap_b32_e32 v228, v229
	v_cvt_pk_bf16_f32 v178, v66, v67
	v_cvt_pk_bf16_f32 v179, v68, v69
	s_waitcnt lgkmcnt(6)
	v_mfma_f32_32x32x16_bf16 v[98:113], v[166:169], v[138:141], v[98:113]
	v_cvt_pk_bf16_f32 v180, v70, v71
	v_cvt_pk_bf16_f32 v181, v72, v73
	v_cvt_pk_bf16_f32 v182, v74, v75
	v_cvt_pk_bf16_f32 v183, v76, v77
	s_waitcnt lgkmcnt(5)
	v_mfma_f32_32x32x16_bf16 v[114:129], v[170:173], v[142:145], v[114:129]
	v_cvt_pk_bf16_f32 v184, v78, v79
	v_cvt_pk_bf16_f32 v185, v80, v81
	v_cvt_pk_bf16_f32 v186, v82, v83
	s_waitcnt lgkmcnt(4)
	v_mfma_f32_32x32x16_bf16 v[98:113], v[174:177], v[142:145], v[98:113]
	v_cvt_pk_bf16_f32 v187, v84, v85
	v_cvt_pk_bf16_f32 v188, v86, v87
	v_cvt_pk_bf16_f32 v189, v88, v89
	s_waitcnt lgkmcnt(3)
	v_mfma_f32_32x32x16_bf16 v[114:129], v[230:233], v[146:149], v[114:129]
	v_cvt_pk_bf16_f32 v190, v90, v91
	v_cvt_pk_bf16_f32 v191, v92, v93
	v_cvt_pk_bf16_f32 v192, v94, v95
	s_waitcnt lgkmcnt(2)
	v_mfma_f32_32x32x16_bf16 v[98:113], v[234:237], v[146:149], v[98:113]
	v_cvt_pk_bf16_f32 v193, v96, v97
	s_nop 1
	v_permlane32_swap_b32_e32 v178, v180
	v_permlane32_swap_b32_e32 v179, v181
	s_waitcnt lgkmcnt(1)
	v_mfma_f32_32x32x16_bf16 v[114:129], v[238:241], v[130:133], v[114:129]
	v_permlane32_swap_b32_e32 v182, v184
	v_permlane32_swap_b32_e32 v183, v185
	v_permlane32_swap_b32_e32 v186, v188
	s_waitcnt lgkmcnt(0)
	v_mfma_f32_32x32x16_bf16 v[98:113], v[242:245], v[130:133], v[98:113]
	v_permlane32_swap_b32_e32 v187, v189
	v_permlane32_swap_b32_e32 v190, v192
	v_permlane32_swap_b32_e32 v191, v193
	s_add_i32 s4, s25, 1
	s_cmp_le_u32 s4, s24
	s_cselect_b64 s[76:77], -1, 0
	s_cmp_gt_u32 s4, s24
	s_cbranch_scc1 .LBB0_1137
	v_add_u32_e32 v162, 0x2000, v194
	v_mov_b32_e32 v163, v195
	v_add_u32_e32 v164, 0x3000, v194
	v_mov_b32_e32 v165, v195
	v_lshlrev_b64 v[170:171], 1, v[162:163]
	v_lshlrev_b64 v[172:173], 1, v[164:165]
	v_lshl_add_u64 v[162:163], s[42:43], 0, v[170:171]
	v_lshl_add_u64 v[166:167], s[42:43], 0, v[172:173]
	v_lshl_add_u64 v[170:171], s[22:23], 0, v[170:171]
	v_lshl_add_u64 v[174:175], s[22:23], 0, v[172:173]
	global_load_dwordx4 v[162:165], v[162:163], off
	s_nop 0
	global_load_dwordx4 v[166:169], v[166:167], off
	s_nop 0
	global_load_dwordx4 v[170:173], v[170:171], off
	s_nop 0
	global_load_dwordx4 v[174:177], v[174:175], off
